# xcd barrier: completing leader releases every XCD generation word itself; other leaders wait on their own XGEN and no longer forward (one hop less on release path)
# speedup vs baseline: 1.0060x; 1.0060x over previous
.LBB0_472:
	s_andn2_saveexec_b64 s[2:3], s[2:3]
	s_cbranch_execz .LBB0_492
	s_mov_b64 s[2:3], exec
	buffer_wbl2 sc1
	v_mov_b32_e32 v6, v1
	s_waitcnt lgkmcnt(0)
	s_waitcnt vmcnt(0)
	v_mbcnt_lo_u32_b32 v1, s2, 0
	v_mbcnt_hi_u32_b32 v1, s3, v1
	v_cmp_eq_u32_e32 vcc, 0, v1
	s_and_saveexec_b64 s[36:37], vcc
	s_cbranch_execz .LBB0_475
	s_bcnt1_i32_b64 s2, s[2:3]
	v_mov_b32_e32 v2, s2
	v_readlane_b32 s2, v246, 55
	v_readlane_b32 s3, v246, 56
	s_nop 4
	global_atomic_add v2, v163, v2, s[2:3] sc0
.LBB0_475:
	s_or_b64 exec, exec, s[36:37]
	s_waitcnt vmcnt(0)
	v_readfirstlane_b32 s2, v2
	v_cvt_f32_u32_e32 v2, v0
	v_sub_u32_e32 v3, 0, v0
	v_add_u32_e32 v1, s2, v1
	v_readlane_b32 s2, v246, 57
	v_rcp_iflag_f32_e32 v2, v2
	v_readlane_b32 s3, v246, 58
	s_mov_b64 s[36:37], -1
	v_mul_f32_e32 v2, 0x4f7ffffe, v2
	v_cvt_u32_f32_e32 v2, v2
	v_mul_lo_u32 v3, v3, v2
	v_mul_hi_u32 v3, v2, v3
	v_add_u32_e32 v2, v2, v3
	v_mul_hi_u32 v2, v1, v2
	v_mul_lo_u32 v3, v2, v0
	v_sub_u32_e32 v3, v1, v3
	v_cmp_ge_u32_e32 vcc, v3, v0
	v_add_u32_e32 v4, 1, v2
	v_add_u32_e32 v1, 1, v1
	v_cndmask_b32_e32 v2, v2, v4, vcc
	v_sub_u32_e32 v4, v3, v0
	v_cndmask_b32_e32 v3, v3, v4, vcc
	v_cmp_ge_u32_e32 vcc, v3, v0
	v_add_u32_e32 v3, 1, v2
	s_nop 0
	v_cndmask_b32_e32 v2, v2, v3, vcc
	v_mul_lo_u32 v3, v0, v2
	v_add_u32_e32 v0, v3, v0
	v_cmp_ne_u32_e32 vcc, v1, v0
	v_mov_b64_e32 v[0:1], s[2:3]
	s_and_saveexec_b64 s[2:3], vcc
	s_cbranch_execz .LBB0_487
	v_readlane_b32 s4, v246, 53
	v_readlane_b32 s5, v246, 54
	s_mov_b64 s[38:39], 0
	s_nop 3
	global_load_dword v0, v163, s[4:5] sc1
	s_waitcnt vmcnt(0)
	v_cmp_eq_u32_e32 vcc, v0, v6
	s_and_saveexec_b64 s[36:37], vcc
	s_cbranch_execz .LBB0_486
	s_mov_b32 s4, 1
	s_branch .LBB0_479

.LBB0_481:
	v_readlane_b32 s6, v246, 53
	v_readlane_b32 s7, v246, 54
	s_add_i32 s4, s4, 1
	s_mov_b64 s[48:49], -1
	s_nop 2
	global_load_dword v0, v163, s[6:7] sc1
	s_waitcnt vmcnt(0)
	v_cmp_ne_u32_e32 vcc, v0, v6
	s_orn2_b64 s[42:43], vcc, exec
	s_branch .LBB0_478

.LBB0_487:
	s_or_b64 exec, exec, s[2:3]
	s_and_saveexec_b64 s[2:3], s[36:37]
	s_cbranch_execz .LBB0_489
	global_atomic_add v[0:1], v202, off
	s_add_u32 s6, s84, 0x182400
	s_addc_u32 s7, s85, 0
	global_atomic_add v163, v202, s[6:7]
	global_atomic_add v163, v202, s[6:7] offset:256
	global_atomic_add v163, v202, s[6:7] offset:512
	global_atomic_add v163, v202, s[6:7] offset:768
	global_atomic_add v163, v202, s[6:7] offset:1024
	global_atomic_add v163, v202, s[6:7] offset:1280
	global_atomic_add v163, v202, s[6:7] offset:1536
	global_atomic_add v163, v202, s[6:7] offset:1792
	global_atomic_add v163, v202, s[6:7] offset:2048
	global_atomic_add v163, v202, s[6:7] offset:2304
	global_atomic_add v163, v202, s[6:7] offset:2560
	global_atomic_add v163, v202, s[6:7] offset:2816
	global_atomic_add v163, v202, s[6:7] offset:3072
	global_atomic_add v163, v202, s[6:7] offset:3328
	global_atomic_add v163, v202, s[6:7] offset:3584
	global_atomic_add v163, v202, s[6:7] offset:3840
.LBB0_489:
	s_or_b64 exec, exec, s[2:3]
	s_mov_b64 s[2:3], exec
	v_mbcnt_lo_u32_b32 v0, s2, 0
	v_mbcnt_hi_u32_b32 v0, s3, v0
	v_cmp_eq_u32_e32 vcc, 0, v0
	s_waitcnt vmcnt(0)
	buffer_inv sc1
	s_and_saveexec_b64 s[36:37], vcc
	s_cbranch_execz .LBB0_491
	s_bcnt1_i32_b64 s2, s[2:3]
	v_mov_b32_e32 v0, s2
	v_readlane_b32 s2, v246, 53
	v_readlane_b32 s3, v246, 54
	s_nop 4
.LBB0_491:
	s_or_b64 exec, exec, s[36:37]
	s_waitcnt vmcnt(0)

.LBB0_565:
	s_or_b64 exec, exec, s[2:3]
	s_mov_b64 s[2:3], exec
	v_mbcnt_lo_u32_b32 v0, s2, 0
	v_mbcnt_hi_u32_b32 v0, s3, v0
	v_cmp_eq_u32_e32 vcc, 0, v0
	s_waitcnt vmcnt(0)
	buffer_inv sc1
	s_and_saveexec_b64 s[36:37], vcc
	s_cbranch_execz .LBB0_567
	s_bcnt1_i32_b64 s2, s[2:3]
	v_mov_b32_e32 v0, s2
	v_readlane_b32 s2, v246, 53
	v_readlane_b32 s3, v246, 54
	s_nop 4
.LBB0_567:
	s_or_b64 exec, exec, s[36:37]
	s_waitcnt vmcnt(0)

.LBB0_624:
	s_or_b64 exec, exec, s[36:37]
	v_cvt_f32_u32_e32 v3, v0
	s_waitcnt vmcnt(0)
	v_readfirstlane_b32 s2, v2
	v_sub_u32_e32 v2, 0, v0
	s_mov_b64 s[36:37], -1
	v_rcp_iflag_f32_e32 v3, v3
	v_add_u32_e32 v1, s2, v1
	v_add_u32_e32 v4, 1, v1
	v_readlane_b32 s2, v246, 57
	v_mul_f32_e32 v3, 0x4f7ffffe, v3
	v_cvt_u32_f32_e32 v3, v3
	v_readlane_b32 s3, v246, 58
	v_mul_lo_u32 v2, v2, v3
	v_mul_hi_u32 v2, v3, v2
	v_add_u32_e32 v2, v3, v2
	v_mul_hi_u32 v2, v1, v2
	v_mul_lo_u32 v3, v2, v0
	v_sub_u32_e32 v1, v1, v3
	v_add_u32_e32 v5, 1, v2
	v_sub_u32_e32 v3, v1, v0
	v_cmp_ge_u32_e32 vcc, v1, v0
	s_nop 1
	v_cndmask_b32_e32 v2, v2, v5, vcc
	v_cndmask_b32_e32 v1, v1, v3, vcc
	v_add_u32_e32 v3, 1, v2
	v_cmp_ge_u32_e32 vcc, v1, v0
	s_nop 1
	v_cndmask_b32_e32 v2, v2, v3, vcc
	v_mul_lo_u32 v1, v0, v2
	v_add_u32_e32 v0, v1, v0
	v_cmp_ne_u32_e32 vcc, v4, v0
	v_mov_b64_e32 v[0:1], s[2:3]
	s_and_saveexec_b64 s[2:3], vcc
	s_cbranch_execz .LBB0_636
	v_readlane_b32 s4, v246, 53
	v_readlane_b32 s5, v246, 54
	s_mov_b64 s[38:39], 0
	s_nop 3
	global_load_dword v0, v163, s[4:5] sc1
	s_waitcnt vmcnt(0)
	v_cmp_eq_u32_e32 vcc, v0, v6
	s_and_saveexec_b64 s[36:37], vcc
	s_cbranch_execz .LBB0_635
	s_mov_b32 s4, 1
	s_branch .LBB0_628

.LBB0_638:
	s_or_b64 exec, exec, s[2:3]
	s_mov_b64 s[2:3], exec
	v_mbcnt_lo_u32_b32 v0, s2, 0
	v_mbcnt_hi_u32_b32 v0, s3, v0
	v_cmp_eq_u32_e32 vcc, 0, v0
	s_waitcnt vmcnt(0)
	buffer_inv sc1
	s_and_saveexec_b64 s[36:37], vcc
	s_cbranch_execz .LBB0_640
	s_bcnt1_i32_b64 s2, s[2:3]
	v_mov_b32_e32 v0, s2
	v_readlane_b32 s2, v246, 53
	v_readlane_b32 s3, v246, 54
	s_nop 4
.LBB0_640:
	s_or_b64 exec, exec, s[36:37]
	s_waitcnt vmcnt(0)

.LBB0_743:
	s_andn2_saveexec_b64 s[4:5], s[36:37]
	s_cbranch_execz .LBB0_763
	s_mov_b64 s[36:37], exec
	buffer_wbl2 sc1
	v_mov_b32_e32 v6, v1
	s_waitcnt lgkmcnt(0)
	s_waitcnt vmcnt(0)
	v_mbcnt_lo_u32_b32 v1, s36, 0
	v_mbcnt_hi_u32_b32 v1, s37, v1
	v_cmp_eq_u32_e32 vcc, 0, v1
	s_and_saveexec_b64 s[38:39], vcc
	s_cbranch_execz .LBB0_746
	s_bcnt1_i32_b64 s4, s[36:37]
	v_mov_b32_e32 v2, s4
	v_readlane_b32 s4, v246, 55
	v_readlane_b32 s5, v246, 56
	s_nop 4
	global_atomic_add v2, v163, v2, s[4:5] sc0
.LBB0_746:
	s_or_b64 exec, exec, s[38:39]
	s_waitcnt vmcnt(0)
	v_readfirstlane_b32 s4, v2
	v_cvt_f32_u32_e32 v2, v0
	v_sub_u32_e32 v3, 0, v0
	v_add_u32_e32 v1, s4, v1
	v_readlane_b32 s4, v246, 57
	v_rcp_iflag_f32_e32 v2, v2
	v_readlane_b32 s5, v246, 58
	s_mov_b64 s[38:39], -1
	v_mul_f32_e32 v2, 0x4f7ffffe, v2
	v_cvt_u32_f32_e32 v2, v2
	v_mul_lo_u32 v3, v3, v2
	v_mul_hi_u32 v3, v2, v3
	v_add_u32_e32 v2, v2, v3
	v_mul_hi_u32 v2, v1, v2
	v_mul_lo_u32 v3, v2, v0
	v_sub_u32_e32 v3, v1, v3
	v_cmp_ge_u32_e32 vcc, v3, v0
	v_add_u32_e32 v4, 1, v2
	v_add_u32_e32 v1, 1, v1
	v_cndmask_b32_e32 v2, v2, v4, vcc
	v_sub_u32_e32 v4, v3, v0
	v_cndmask_b32_e32 v3, v3, v4, vcc
	v_cmp_ge_u32_e32 vcc, v3, v0
	v_add_u32_e32 v3, 1, v2
	s_nop 0
	v_cndmask_b32_e32 v2, v2, v3, vcc
	v_mul_lo_u32 v3, v0, v2
	v_add_u32_e32 v0, v3, v0
	v_cmp_ne_u32_e32 vcc, v1, v0
	v_mov_b64_e32 v[0:1], s[4:5]
	s_and_saveexec_b64 s[36:37], vcc
	s_cbranch_execz .LBB0_758
	v_readlane_b32 s4, v246, 53
	v_readlane_b32 s5, v246, 54
	s_mov_b64 s[40:41], 0
	s_nop 3
	global_load_dword v0, v163, s[4:5] sc1
	s_waitcnt vmcnt(0)
	v_cmp_eq_u32_e32 vcc, v0, v6
	s_and_saveexec_b64 s[38:39], vcc
	s_cbranch_execz .LBB0_757
	s_mov_b32 s4, 1
	s_branch .LBB0_750

.LBB0_752:
	v_readlane_b32 s6, v246, 53
	v_readlane_b32 s7, v246, 54
	s_add_i32 s4, s4, 1
	s_mov_b64 s[50:51], -1
	s_nop 2
	global_load_dword v0, v163, s[6:7] sc1
	s_waitcnt vmcnt(0)
	v_cmp_ne_u32_e32 vcc, v0, v6
	s_orn2_b64 s[48:49], vcc, exec
	s_branch .LBB0_749

.LBB0_758:
	s_or_b64 exec, exec, s[36:37]
	s_and_saveexec_b64 s[36:37], s[38:39]
	s_cbranch_execz .LBB0_760
	global_atomic_add v[0:1], v202, off
	s_add_u32 s6, s84, 0x182400
	s_addc_u32 s7, s85, 0
	global_atomic_add v163, v202, s[6:7]
	global_atomic_add v163, v202, s[6:7] offset:256
	global_atomic_add v163, v202, s[6:7] offset:512
	global_atomic_add v163, v202, s[6:7] offset:768
	global_atomic_add v163, v202, s[6:7] offset:1024
	global_atomic_add v163, v202, s[6:7] offset:1280
	global_atomic_add v163, v202, s[6:7] offset:1536
	global_atomic_add v163, v202, s[6:7] offset:1792
	global_atomic_add v163, v202, s[6:7] offset:2048
	global_atomic_add v163, v202, s[6:7] offset:2304
	global_atomic_add v163, v202, s[6:7] offset:2560
	global_atomic_add v163, v202, s[6:7] offset:2816
	global_atomic_add v163, v202, s[6:7] offset:3072
	global_atomic_add v163, v202, s[6:7] offset:3328
	global_atomic_add v163, v202, s[6:7] offset:3584
	global_atomic_add v163, v202, s[6:7] offset:3840
.LBB0_760:
	s_or_b64 exec, exec, s[36:37]
	s_mov_b64 s[36:37], exec
	v_mbcnt_lo_u32_b32 v0, s36, 0
	v_mbcnt_hi_u32_b32 v0, s37, v0
	v_cmp_eq_u32_e32 vcc, 0, v0
	s_waitcnt vmcnt(0)
	buffer_inv sc1
	s_and_saveexec_b64 s[38:39], vcc
	s_cbranch_execz .LBB0_762
	s_bcnt1_i32_b64 s4, s[36:37]
	v_mov_b32_e32 v0, s4
	v_readlane_b32 s4, v246, 53
	v_readlane_b32 s5, v246, 54
	s_nop 4
.LBB0_762:
	s_or_b64 exec, exec, s[38:39]
	s_waitcnt vmcnt(0)

.LBB0_877:
	s_or_b64 exec, exec, s[36:37]
	s_mov_b64 s[36:37], exec
	v_mbcnt_lo_u32_b32 v0, s36, 0
	v_mbcnt_hi_u32_b32 v0, s37, v0
	v_cmp_eq_u32_e32 vcc, 0, v0
	s_waitcnt vmcnt(0)
	buffer_inv sc1
	s_and_saveexec_b64 s[38:39], vcc
	s_cbranch_execz .LBB0_879
	s_bcnt1_i32_b64 s4, s[36:37]
	v_mov_b32_e32 v0, s4
	v_readlane_b32 s4, v246, 53
	v_readlane_b32 s5, v246, 54
	s_nop 4
.LBB0_879:
	s_or_b64 exec, exec, s[38:39]
	s_waitcnt vmcnt(0)

.LBB0_970:
	s_or_b64 exec, exec, s[36:37]
	s_mov_b64 s[36:37], exec
	v_mbcnt_lo_u32_b32 v0, s36, 0
	v_mbcnt_hi_u32_b32 v0, s37, v0
	v_cmp_eq_u32_e32 vcc, 0, v0
	s_waitcnt vmcnt(0)
	buffer_inv sc1
	s_and_saveexec_b64 s[38:39], vcc
	s_cbranch_execz .LBB0_972
	s_bcnt1_i32_b64 s4, s[36:37]
	v_mov_b32_e32 v0, s4
	v_readlane_b32 s4, v246, 53
	v_readlane_b32 s5, v246, 54
	s_nop 4
.LBB0_972:
	s_or_b64 exec, exec, s[38:39]
	s_waitcnt vmcnt(0)

.LBB0_1065:
	s_or_b64 exec, exec, s[2:3]
	s_mov_b64 s[2:3], exec
	v_mbcnt_lo_u32_b32 v0, s2, 0
	v_mbcnt_hi_u32_b32 v0, s3, v0
	v_cmp_eq_u32_e32 vcc, 0, v0
	s_waitcnt vmcnt(0)
	buffer_inv sc1
	s_and_saveexec_b64 s[36:37], vcc
	s_cbranch_execz .LBB0_1067
	s_bcnt1_i32_b64 s2, s[2:3]
	v_mov_b32_e32 v0, s2
	v_readlane_b32 s2, v246, 53
	v_readlane_b32 s3, v246, 54
	s_nop 4
.LBB0_1067:
	s_or_b64 exec, exec, s[36:37]
	s_waitcnt vmcnt(0)

.LBB0_1126:
	s_or_b64 exec, exec, s[2:3]
	s_mov_b64 s[2:3], exec
	v_mbcnt_lo_u32_b32 v0, s2, 0
	v_mbcnt_hi_u32_b32 v0, s3, v0
	v_cmp_eq_u32_e32 vcc, 0, v0
	s_waitcnt vmcnt(0)
	buffer_inv sc1
	s_and_saveexec_b64 s[36:37], vcc
	s_cbranch_execz .LBB0_1128
	s_bcnt1_i32_b64 s2, s[2:3]
	v_mov_b32_e32 v0, s2
	v_readlane_b32 s2, v246, 53
	v_readlane_b32 s3, v246, 54
	s_nop 4
.LBB0_1128:
	s_or_b64 exec, exec, s[36:37]
	s_waitcnt vmcnt(0)

.LBB0_1194:
	s_or_b64 exec, exec, s[2:3]
	s_mov_b64 s[2:3], exec
	v_mbcnt_lo_u32_b32 v0, s2, 0
	v_mbcnt_hi_u32_b32 v0, s3, v0
	v_cmp_eq_u32_e32 vcc, 0, v0
	s_waitcnt vmcnt(0)
	buffer_inv sc1
	s_and_saveexec_b64 s[36:37], vcc
	s_cbranch_execz .LBB0_1196
	s_bcnt1_i32_b64 s2, s[2:3]
	v_mov_b32_e32 v0, s2
	v_readlane_b32 s2, v246, 53
	v_readlane_b32 s3, v246, 54
	s_nop 4
.LBB0_1196:
	s_or_b64 exec, exec, s[36:37]
	s_waitcnt vmcnt(0)

.LBB0_1305:
	s_or_b64 exec, exec, s[2:3]
	s_mov_b64 s[2:3], exec
	v_mbcnt_lo_u32_b32 v0, s2, 0
	v_mbcnt_hi_u32_b32 v0, s3, v0
	v_cmp_eq_u32_e32 vcc, 0, v0
	s_waitcnt vmcnt(0)
	buffer_inv sc1
	s_and_saveexec_b64 s[36:37], vcc
	s_cbranch_execz .LBB0_1307
	s_bcnt1_i32_b64 s2, s[2:3]
	v_mov_b32_e32 v0, s2
	v_readlane_b32 s2, v246, 53
	v_readlane_b32 s3, v246, 54
	s_nop 4
.LBB0_1307:
	s_or_b64 exec, exec, s[36:37]
	s_waitcnt vmcnt(0)

.LBB0_1344:
	s_mov_b64 s[2:3], exec
	buffer_wbl2 sc1
	v_mov_b32_e32 v6, v1
	s_waitcnt lgkmcnt(0)
	s_waitcnt vmcnt(0)
	v_mbcnt_lo_u32_b32 v1, s2, 0
	v_mbcnt_hi_u32_b32 v1, s3, v1
	v_cmp_eq_u32_e32 vcc, 0, v1
	s_and_saveexec_b64 s[36:37], vcc
	s_cbranch_execz .LBB0_1346
	s_bcnt1_i32_b64 s2, s[2:3]
	v_mov_b32_e32 v2, s2
	v_readlane_b32 s2, v246, 55
	v_readlane_b32 s3, v246, 56
	s_nop 4
	global_atomic_add v2, v163, v2, s[2:3] sc0

.LBB0_1361:
	s_bcnt1_i32_b64 s2, s[2:3]
	v_mov_b32_e32 v0, s2
	v_readlane_b32 s2, v246, 53
	v_readlane_b32 s3, v246, 54
	s_nop 4
	s_getpc_b64 s[98:99]
